# v24 plus: when a CU's own attention queue is exhausted it reads all 8 per-XCD queue counters in one batch and skips already-exhausted foreign queues instead of 7 serial failing fetch-add pops
# speedup vs baseline: 1.0022x; 1.0022x over previous
.LBB0_190:
	s_add_i32 s43, s43, 1
	s_add_i32 s44, s44, 1
	s_cmp_eq_u32 s43, 8
	s_cbranch_scc1 .LBB0_232
	s_cmp_lg_u32 s43, 1
	s_cbranch_scc1 .Lq_check
	v_readlane_b32 s100, v252, 42
	v_readlane_b32 s101, v252, 43
	s_lshl_b32 s2, s42, 8
	s_add_u32 s100, s100, s2
	s_addc_u32 s101, s101, 0
	s_nop 4
	global_load_dword v0, v169, s[100:101] sc1
	global_load_dword v1, v169, s[100:101] offset:256 sc1
	global_load_dword v2, v169, s[100:101] offset:512 sc1
	global_load_dword v3, v169, s[100:101] offset:768 sc1
	global_load_dword v4, v169, s[100:101] offset:1024 sc1
	global_load_dword v5, v169, s[100:101] offset:1280 sc1
	global_load_dword v6, v169, s[100:101] offset:1536 sc1
	global_load_dword v7, v169, s[100:101] offset:1792 sc1
	s_waitcnt vmcnt(0)
	s_sub_u32 s2, 0x84, s36
	s_mov_b32 s101, 0
	v_readfirstlane_b32 s3, v0
	s_cmp_ge_u32 s3, s2
	s_cselect_b32 s3, 1, 0
	s_or_b32 s101, s101, s3
	v_readfirstlane_b32 s3, v1
	s_cmp_ge_u32 s3, s2
	s_cselect_b32 s3, 2, 0
	s_or_b32 s101, s101, s3
	v_readfirstlane_b32 s3, v2
	s_cmp_ge_u32 s3, s2
	s_cselect_b32 s3, 4, 0
	s_or_b32 s101, s101, s3
	v_readfirstlane_b32 s3, v3
	s_cmp_ge_u32 s3, s2
	s_cselect_b32 s3, 8, 0
	s_or_b32 s101, s101, s3
	v_readfirstlane_b32 s3, v4
	s_cmp_ge_u32 s3, s2
	s_cselect_b32 s3, 16, 0
	s_or_b32 s101, s101, s3
	v_readfirstlane_b32 s3, v5
	s_cmp_ge_u32 s3, s2
	s_cselect_b32 s3, 32, 0
	s_or_b32 s101, s101, s3
	v_readfirstlane_b32 s3, v6
	s_cmp_ge_u32 s3, s2
	s_cselect_b32 s3, 64, 0
	s_or_b32 s101, s101, s3
	v_readfirstlane_b32 s3, v7
	s_cmp_ge_u32 s3, s2
	s_cselect_b32 s3, 128, 0
	s_or_b32 s101, s101, s3
	v_mov_b32_e32 v0, s101
	v_mov_b32_e32 v1, s38
	s_and_saveexec_b64 s[2:3], s[0:1]
	ds_write_b32 v1, v0 offset:4
	s_mov_b64 exec, s[2:3]
	s_waitcnt lgkmcnt(0)
	s_barrier
	ds_read_b32 v0, v1 offset:4
	s_waitcnt lgkmcnt(0)
	v_readfirstlane_b32 s101, v0
	s_barrier
.Lq_check:
	s_and_b32 s2, s44, 7
	s_lshr_b32 s2, s101, s2
	s_and_b32 s2, s2, 1
	s_cmp_eq_u32 s2, 1
	s_cbranch_scc1 .LBB0_190
